# adds: layer-0 out-projection epilogue fused with the residual update (x1 = XG0/gg0 + g*acc in f32, XG rewritten in place, row sum-of-squares by f32 atomics); separate resid0 pass and its grid barrier
# speedup vs baseline: 1.0566x; 1.0262x over previous
.LBB0_593:
	s_or_b64 exec, exec, s[42:43]
	v_mul_f32_e32 v8, 0xbfb8aa3b, v8
	v_exp_f32_e32 v10, v8
	s_mov_b32 s1, 0x3f2aaaab
	s_mov_b32 s6, 0x3f317218
	s_mov_b32 s7, 0x7f800000
	v_add_f32_e32 v11, 1.0, v10
	v_frexp_mant_f32_e32 v13, v11
	v_cvt_f64_f32_e32 v[8:9], v11
	v_add_f32_e32 v12, -1.0, v11
	v_frexp_exp_i32_f64_e32 v8, v[8:9]
	v_cmp_gt_f32_e32 vcc, s1, v13
	v_sub_f32_e32 v14, v12, v11
	v_sub_f32_e32 v12, v10, v12
	v_subbrev_co_u32_e32 v8, vcc, 0, v8, vcc
	v_add_f32_e32 v14, 1.0, v14
	v_sub_u32_e32 v9, 0, v8
	v_add_f32_e32 v12, v12, v14
	v_ldexp_f32 v11, v11, v9
	v_ldexp_f32 v9, v12, v9
	v_add_f32_e32 v12, -1.0, v11
	v_add_f32_e32 v15, 1.0, v11
	v_add_f32_e32 v13, 1.0, v12
	v_add_f32_e32 v16, -1.0, v15
	v_sub_f32_e32 v13, v11, v13
	v_sub_f32_e32 v11, v11, v16
	v_add_f32_e32 v13, v9, v13
	v_add_f32_e32 v9, v9, v11
	v_add_f32_e32 v11, v15, v9
	v_rcp_f32_e32 v16, v11
	v_add_f32_e32 v14, v12, v13
	v_sub_f32_e32 v12, v14, v12
	v_sub_f32_e32 v12, v13, v12
	v_sub_f32_e32 v13, v11, v15
	v_sub_f32_e32 v9, v9, v13
	v_mul_f32_e32 v13, v14, v16
	v_mul_f32_e32 v15, v11, v13
	v_fma_f32 v17, v13, v11, -v15
	v_fmac_f32_e32 v17, v13, v9
	v_add_f32_e32 v18, v15, v17
	v_sub_f32_e32 v19, v14, v18
	v_sub_f32_e32 v14, v14, v19
	v_sub_f32_e32 v15, v18, v15
	v_sub_f32_e32 v14, v14, v18
	v_add_f32_e32 v12, v12, v14
	v_sub_f32_e32 v14, v15, v17
	v_add_f32_e32 v12, v14, v12
	v_add_f32_e32 v14, v19, v12
	v_mul_f32_e32 v15, v16, v14
	v_mul_f32_e32 v17, v11, v15
	v_fma_f32 v11, v15, v11, -v17
	v_fmac_f32_e32 v11, v15, v9
	v_sub_f32_e32 v9, v19, v14
	v_add_f32_e32 v9, v12, v9
	v_add_f32_e32 v12, v17, v11
	v_sub_f32_e32 v18, v14, v12
	v_sub_f32_e32 v14, v14, v18
	v_sub_f32_e32 v17, v12, v17
	v_sub_f32_e32 v12, v14, v12
	v_add_f32_e32 v9, v9, v12
	v_sub_f32_e32 v11, v17, v11
	v_cvt_f32_i32_e32 v8, v8
	v_add_f32_e32 v9, v11, v9
	v_add_f32_e32 v11, v13, v15
	v_add_f32_e32 v9, v18, v9
	v_sub_f32_e32 v12, v11, v13
	v_mul_f32_e32 v9, v16, v9
	v_sub_f32_e32 v12, v15, v12
	v_add_f32_e32 v9, v12, v9
	v_mul_f32_e32 v15, 0x3f317218, v8
	v_add_f32_e32 v12, v11, v9
	v_fma_f32 v16, v8, s6, -v15
	v_mul_f32_e32 v13, v12, v12
	v_fmac_f32_e32 v16, 0xb102e308, v8
	v_sub_f32_e32 v8, v12, v11
	v_fmamk_f32 v14, v13, 0x3e9b6dac, v179
	v_sub_f32_e32 v8, v9, v8
	v_add_f32_e32 v9, v15, v16
	v_fmaak_f32 v14, v13, v14, 0x3f2aaada
	v_sub_f32_e32 v11, v9, v15
	v_ldexp_f32 v15, v12, 1
	v_mul_f32_e32 v12, v12, v13
	v_mul_f32_e32 v12, v12, v14
	v_add_f32_e32 v13, v15, v12
	v_sub_f32_e32 v14, v13, v15
	v_ldexp_f32 v8, v8, 1
	v_sub_f32_e32 v12, v12, v14
	v_add_f32_e32 v8, v8, v12
	v_add_f32_e32 v12, v13, v8
	v_sub_f32_e32 v13, v12, v13
	v_sub_f32_e32 v8, v8, v13
	v_add_f32_e32 v13, v9, v12
	v_sub_f32_e32 v14, v13, v9
	v_sub_f32_e32 v15, v13, v14
	v_sub_f32_e32 v11, v16, v11
	v_sub_f32_e32 v9, v9, v15
	v_sub_f32_e32 v12, v12, v14
	v_add_f32_e32 v9, v12, v9
	v_add_f32_e32 v12, v11, v8
	v_sub_f32_e32 v14, v12, v11
	v_sub_f32_e32 v15, v12, v14
	v_sub_f32_e32 v11, v11, v15
	v_sub_f32_e32 v8, v8, v14
	v_add_f32_e32 v9, v12, v9
	v_add_f32_e32 v8, v8, v11
	v_add_f32_e32 v11, v13, v9
	v_sub_f32_e32 v12, v11, v13
	v_sub_f32_e32 v9, v9, v12
	v_add_f32_e32 v8, v8, v9
	v_mul_f32_e32 v7, 0xbfb8aa3b, v7
	v_add_f32_e32 v8, v11, v8
	v_cmp_neq_f32_e32 vcc, s7, v10
	v_exp_f32_e32 v7, v7
	s_mov_b32 s8, 0x33800000
	v_cndmask_b32_e32 v8, v182, v8, vcc
	v_cmp_ngt_f32_e32 vcc, -1.0, v10
	v_cmp_gt_u32_e64 s[42:43], 32, v3
	v_lshl_add_u64 v[72:73], s[44:45], 0, v[144:145]
	v_cndmask_b32_e32 v8, v183, v8, vcc
	v_cmp_neq_f32_e32 vcc, -1.0, v10
	s_mov_b32 s4, 0
	s_waitcnt lgkmcnt(0)
	v_cndmask_b32_e32 v8, v184, v8, vcc
	v_cmp_lt_f32_e64 vcc, |v10|, s8
	s_barrier
	s_nop 0
	v_cndmask_b32_e32 v8, v8, v10, vcc
	v_add_f32_e32 v10, 1.0, v7
	v_mul_f32_e32 v167, 0xc1000000, v8
	v_add_f32_e32 v8, -1.0, v10
	v_sub_f32_e32 v9, v8, v10
	v_add_f32_e32 v9, 1.0, v9
	v_sub_f32_e32 v8, v7, v8
	v_add_f32_e32 v11, v8, v9
	v_frexp_mant_f32_e32 v12, v10
	v_cvt_f64_f32_e32 v[8:9], v10
	v_frexp_exp_i32_f64_e32 v8, v[8:9]
	v_cmp_gt_f32_e32 vcc, s1, v12
	v_readlane_b32 s1, v242, 2
	s_nop 0
	v_subbrev_co_u32_e32 v8, vcc, 0, v8, vcc
	v_sub_u32_e32 v9, 0, v8
	v_ldexp_f32 v10, v10, v9
	v_ldexp_f32 v9, v11, v9
	v_add_f32_e32 v11, -1.0, v10
	v_add_f32_e32 v14, 1.0, v10
	v_add_f32_e32 v12, 1.0, v11
	v_add_f32_e32 v15, -1.0, v14
	v_sub_f32_e32 v12, v10, v12
	v_sub_f32_e32 v10, v10, v15
	v_add_f32_e32 v12, v9, v12
	v_add_f32_e32 v9, v9, v10
	v_add_f32_e32 v10, v14, v9
	v_rcp_f32_e32 v15, v10
	v_add_f32_e32 v13, v11, v12
	v_sub_f32_e32 v11, v13, v11
	v_sub_f32_e32 v11, v12, v11
	v_sub_f32_e32 v12, v10, v14
	v_sub_f32_e32 v9, v9, v12
	v_mul_f32_e32 v12, v13, v15
	v_mul_f32_e32 v14, v10, v12
	v_fma_f32 v16, v12, v10, -v14
	v_fmac_f32_e32 v16, v12, v9
	v_add_f32_e32 v17, v14, v16
	v_sub_f32_e32 v18, v13, v17
	v_sub_f32_e32 v13, v13, v18
	v_sub_f32_e32 v14, v17, v14
	v_sub_f32_e32 v13, v13, v17
	v_add_f32_e32 v11, v11, v13
	v_sub_f32_e32 v13, v14, v16
	v_add_f32_e32 v11, v13, v11
	v_add_f32_e32 v13, v18, v11
	v_mul_f32_e32 v14, v15, v13
	v_mul_f32_e32 v16, v10, v14
	v_fma_f32 v10, v14, v10, -v16
	v_fmac_f32_e32 v10, v14, v9
	v_sub_f32_e32 v9, v18, v13
	v_add_f32_e32 v9, v11, v9
	v_add_f32_e32 v11, v16, v10
	v_sub_f32_e32 v17, v13, v11
	v_sub_f32_e32 v13, v13, v17
	v_sub_f32_e32 v16, v11, v16
	v_sub_f32_e32 v11, v13, v11
	v_add_f32_e32 v9, v9, v11
	v_sub_f32_e32 v10, v16, v10
	v_cvt_f32_i32_e32 v8, v8
	v_add_f32_e32 v9, v10, v9
	v_add_f32_e32 v10, v12, v14
	v_add_f32_e32 v9, v17, v9
	v_sub_f32_e32 v11, v10, v12
	v_mul_f32_e32 v9, v15, v9
	v_sub_f32_e32 v11, v14, v11
	v_add_f32_e32 v9, v11, v9
	v_mul_f32_e32 v14, 0x3f317218, v8
	v_add_f32_e32 v11, v10, v9
	v_fma_f32 v15, v8, s6, -v14
	v_mul_f32_e32 v12, v11, v11
	v_fmac_f32_e32 v15, 0xb102e308, v8
	v_sub_f32_e32 v8, v11, v10
	v_fmamk_f32 v13, v12, 0x3e9b6dac, v179
	v_sub_f32_e32 v8, v9, v8
	v_add_f32_e32 v9, v14, v15
	v_fmaak_f32 v13, v12, v13, 0x3f2aaada
	v_sub_f32_e32 v10, v9, v14
	v_ldexp_f32 v14, v11, 1
	v_mul_f32_e32 v11, v11, v12
	v_mul_f32_e32 v11, v11, v13
	v_add_f32_e32 v12, v14, v11
	v_sub_f32_e32 v13, v12, v14
	v_ldexp_f32 v8, v8, 1
	v_sub_f32_e32 v11, v11, v13
	v_add_f32_e32 v8, v8, v11
	v_add_f32_e32 v11, v12, v8
	v_sub_f32_e32 v12, v11, v12
	v_sub_f32_e32 v8, v8, v12
	v_add_f32_e32 v12, v9, v11
	v_sub_f32_e32 v13, v12, v9
	v_sub_f32_e32 v14, v12, v13
	v_sub_f32_e32 v10, v15, v10
	v_sub_f32_e32 v9, v9, v14
	v_sub_f32_e32 v11, v11, v13
	v_add_f32_e32 v9, v11, v9
	v_add_f32_e32 v11, v10, v8
	v_sub_f32_e32 v13, v11, v10
	v_sub_f32_e32 v14, v11, v13
	v_sub_f32_e32 v10, v10, v14
	v_sub_f32_e32 v8, v8, v13
	v_add_f32_e32 v9, v11, v9
	v_add_f32_e32 v8, v8, v10
	v_add_f32_e32 v10, v12, v9
	v_sub_f32_e32 v11, v10, v12
	v_sub_f32_e32 v9, v9, v11
	v_add_f32_e32 v8, v8, v9
	v_add_f32_e32 v8, v10, v8
	v_cmp_neq_f32_e32 vcc, s7, v7
	v_lshlrev_b32_e32 v9, 2, v0
	v_and_b32_e32 v9, 60, v9
	v_cndmask_b32_e32 v8, v182, v8, vcc
	v_cmp_ngt_f32_e32 vcc, -1.0, v7
	v_lshlrev_b32_e32 v10, 2, v9
	v_readlane_b32 s6, v242, 3
	v_cndmask_b32_e32 v8, v183, v8, vcc
	v_cmp_neq_f32_e32 vcc, -1.0, v7
	v_add_u32_e32 v170, 0, v10
	v_lshlrev_b32_e32 v171, 1, v9
	v_cndmask_b32_e32 v8, v184, v8, vcc
	v_cmp_lt_f32_e64 vcc, |v7|, s8
	v_add_u32_e32 v9, s6, v10
	v_lshl_add_u32 v169, v158, 3, s1
	v_cndmask_b32_e32 v7, v8, v7, vcc
	v_mul_f32_e32 v168, 0xc1000000, v7
	v_ashrrev_i32_e32 v7, 7, v0
	v_lshlrev_b32_e32 v10, 5, v7
	v_or_b32_e32 v5, v10, v5
	s_movk_i32 s1, 0x90
	v_readlane_b32 s7, v242, 4
	v_mul_lo_u32 v5, v5, s1
	v_lshl_add_u32 v14, v158, 2, s6
	v_add_u32_e32 v172, s7, v171
	v_add_u32_e32 v12, s7, v5
	v_lshlrev_b32_e32 v15, 12, v4
	v_and_b32_e32 v0, 0x1fffff80, v0
	v_lshl_add_u64 v[4:5], s[58:59], 0, v[144:145]
	s_mov_b64 s[6:7], 0x11b80000
	v_lshrrev_b32_e32 v8, 5, v3
	v_lshl_add_u32 v173, v0, 3, v169
	v_lshl_add_u64 v[74:75], v[4:5], 0, s[6:7]
	v_or_b32_e32 v0, 3, v2
	s_movk_i32 s6, 0x110
	v_and_b32_e32 v11, -4, v2
	v_mul_lo_u32 v188, v0, s1
	v_mul_lo_u32 v4, v0, s6
	v_lshl_or_b32 v0, v8, 2, v10
	v_lshl_add_u32 v16, v3, 4, 0
	v_mul_lo_u32 v174, v11, s1
	v_mul_lo_u32 v3, v11, s6
	v_mul_lo_u32 v5, v0, s6
	v_mul_lo_u32 v189, v0, s1
	s_lshl_b32 s1, s5, 7
	v_readlane_b32 s6, v243, 22
	s_add_i32 s1, s1, s6
	v_add_u32_e32 v190, s1, v2
	s_ashr_i32 s1, s0, 31
	s_lshl_b64 s[6:7], s[0:1], 12
	s_add_u32 s6, s58, s6
	v_readlane_b32 s1, v243, 59
	v_lshlrev_b32_e32 v144, 2, v1
	s_addc_u32 s7, s59, s7
	s_add_i32 s1, s1, s5
	v_lshlrev_b32_e32 v13, 4, v8
	v_lshl_add_u64 v[0:1], s[6:7], 0, v[144:145]
	s_mov_b64 s[6:7], 0x162eec40
	s_lshl_b32 s1, s1, 7
	v_cmp_lt_i32_e64 s[44:45], 0, v7
	v_cmp_lt_i32_e64 s[46:47], 1, v7
	v_cmp_lt_i32_e64 s[48:49], 2, v7
	v_cmp_gt_i32_e64 s[50:51], 3, v7
	v_cmp_gt_i32_e64 s[52:53], 2, v7
	v_cmp_gt_i32_e64 s[54:55], 1, v7
	v_lshl_add_u64 v[76:77], v[0:1], 0, s[6:7]
	v_add3_u32 v144, v6, s1, -2
	v_add_u32_e32 v191, s1, v2
	v_add_u32_e32 v192, v9, v3
	v_add_u32_e32 v193, v9, v4
	v_add_u32_e32 v194, v12, v13
	v_add_u32_e32 v195, v14, v5
	v_add_u32_e32 v196, v16, v15
	s_mov_b32 s1, 0
	v_mul_f32_e32 v159, 0xbfb8aa3b, v159
	v_mul_f32_e32 v160, 0xbfb8aa3b, v160
	v_mul_f32_e32 v161, 0xbfb8aa3b, v161
	v_mul_f32_e32 v162, 0xbfb8aa3b, v162
	v_mul_f32_e32 v167, 0x3fb8aa3b, v167
	v_mul_f32_e32 v168, 0x3fb8aa3b, v168
	s_branch .Lcf_entry
	s_branch .LBB0_595

.LBB0_716:
	v_readlane_b32 s98, v242, 47
	s_nop 3
	s_cmp_eq_u32 s98, 0
	s_cbranch_scc1 .Lfe_start
	v_lshl_or_b32 v166, s96, 8, v174
	v_ashrrev_i32_e32 v167, 31, v166
	v_lshl_add_u64 v[100:101], v[166:167], 2, s[44:45]
	global_load_dwordx4 v[104:107], v[100:101], off offset:16
	global_load_dwordx4 v[108:111], v[100:101], off
	global_load_dwordx4 v[96:99], v[100:101], off offset:528
	s_nop 0
	global_load_dwordx4 v[100:103], v[100:101], off offset:512
	v_lshl_add_u32 v170, s92, 8, v172
	v_ashrrev_i32_e32 v171, 31, v170
	v_lshlrev_b64 v[168:169], 12, v[170:171]
	v_lshl_add_u64 v[190:191], s[38:39], 0, v[168:169]
	v_lshlrev_b64 v[168:169], 1, v[166:167]
	v_lshl_add_u64 v[166:167], v[190:191], 0, v[168:169]
	s_mov_b64 s[10:11], 0x80000
	s_mov_b64 s[58:59], -1
	s_waitcnt vmcnt(0)
	v_pk_mul_f32 v[190:191], v[138:139], v[106:107]
	v_pk_mul_f32 v[142:143], v[142:143], v[110:111]
	v_pk_mul_f32 v[140:141], v[140:141], v[108:109]
	v_pk_mul_f32 v[138:139], v[136:137], v[104:105]
	v_cvt_pk_bf16_f32 v136, v140, v141
	v_cvt_pk_bf16_f32 v137, v142, v143
	v_pk_mul_f32 v[132:133], v[132:133], v[100:101]
	v_cvt_pk_bf16_f32 v138, v138, v139
	v_cvt_pk_bf16_f32 v139, v190, v191
	global_store_dwordx4 v[166:167], v[136:139], off
	v_pk_mul_f32 v[134:135], v[134:135], v[102:103]
	v_pk_mul_f32 v[126:127], v[126:127], v[110:111]
	v_pk_mul_f32 v[136:137], v[130:131], v[98:99]
	v_pk_mul_f32 v[130:131], v[128:129], v[96:97]
	v_cvt_pk_bf16_f32 v128, v132, v133
	v_cvt_pk_bf16_f32 v129, v134, v135
	v_pk_mul_f32 v[124:125], v[124:125], v[108:109]
	v_cvt_pk_bf16_f32 v130, v130, v131
	v_cvt_pk_bf16_f32 v131, v136, v137
	global_store_dwordx4 v[166:167], v[128:131], off offset:256
	v_pk_mul_f32 v[116:117], v[116:117], v[100:101]
	v_pk_mul_f32 v[118:119], v[118:119], v[102:103]
	v_or_b32_e32 v128, 16, v170
	v_ashrrev_i32_e32 v129, 31, v128
	v_lshlrev_b64 v[128:129], 12, v[128:129]
	v_lshl_add_u64 v[128:129], s[38:39], 0, v[128:129]
	v_lshl_add_u64 v[128:129], v[128:129], 0, v[168:169]
	v_pk_mul_f32 v[130:131], v[122:123], v[106:107]
	v_pk_mul_f32 v[122:123], v[120:121], v[104:105]
	v_cvt_pk_bf16_f32 v120, v124, v125
	v_cvt_pk_bf16_f32 v121, v126, v127
	v_pk_mul_f32 v[94:95], v[94:95], v[110:111]
	v_cvt_pk_bf16_f32 v122, v122, v123
	v_cvt_pk_bf16_f32 v123, v130, v131
	global_store_dwordx4 v[128:129], v[120:123], off
	v_pk_mul_f32 v[92:93], v[92:93], v[108:109]
	v_pk_mul_f32 v[84:85], v[84:85], v[100:101]
	v_pk_mul_f32 v[120:121], v[114:115], v[98:99]
	v_pk_mul_f32 v[114:115], v[112:113], v[96:97]
	v_cvt_pk_bf16_f32 v112, v116, v117
	v_cvt_pk_bf16_f32 v113, v118, v119
	v_pk_mul_f32 v[86:87], v[86:87], v[102:103]
	v_cvt_pk_bf16_f32 v114, v114, v115
	v_cvt_pk_bf16_f32 v115, v120, v121
	global_store_dwordx4 v[128:129], v[112:115], off offset:256
	v_pk_mul_f32 v[78:79], v[78:79], v[110:111]
	v_pk_mul_f32 v[76:77], v[76:77], v[108:109]
	v_or_b32_e32 v112, 32, v170
	v_ashrrev_i32_e32 v113, 31, v112
	v_lshlrev_b64 v[112:113], 12, v[112:113]
	v_lshl_add_u64 v[112:113], s[38:39], 0, v[112:113]
	v_lshl_add_u64 v[112:113], v[112:113], 0, v[168:169]
	v_pk_mul_f32 v[114:115], v[90:91], v[106:107]
	v_pk_mul_f32 v[90:91], v[88:89], v[104:105]
	v_cvt_pk_bf16_f32 v88, v92, v93
	v_cvt_pk_bf16_f32 v89, v94, v95
	v_pk_mul_f32 v[70:71], v[70:71], v[102:103]
	v_cvt_pk_bf16_f32 v90, v90, v91
	v_cvt_pk_bf16_f32 v91, v114, v115
	global_store_dwordx4 v[112:113], v[88:91], off
	v_pk_mul_f32 v[68:69], v[68:69], v[100:101]
	v_pk_mul_f32 v[60:61], v[60:61], v[108:109]
	v_pk_mul_f32 v[88:89], v[82:83], v[98:99]
	v_pk_mul_f32 v[82:83], v[80:81], v[96:97]
	v_cvt_pk_bf16_f32 v80, v84, v85
	v_cvt_pk_bf16_f32 v81, v86, v87
	v_pk_mul_f32 v[62:63], v[62:63], v[110:111]
	v_cvt_pk_bf16_f32 v82, v82, v83
	v_cvt_pk_bf16_f32 v83, v88, v89
	global_store_dwordx4 v[112:113], v[80:83], off offset:256
	v_pk_mul_f32 v[54:55], v[54:55], v[102:103]
	v_pk_mul_f32 v[52:53], v[52:53], v[100:101]
	v_or_b32_e32 v80, 48, v170
	v_ashrrev_i32_e32 v81, 31, v80
	v_lshlrev_b64 v[80:81], 12, v[80:81]
	v_lshl_add_u64 v[80:81], s[38:39], 0, v[80:81]
	v_lshl_add_u64 v[80:81], v[80:81], 0, v[168:169]
	v_pk_mul_f32 v[82:83], v[74:75], v[106:107]
	v_pk_mul_f32 v[74:75], v[72:73], v[104:105]
	v_cvt_pk_bf16_f32 v72, v76, v77
	v_cvt_pk_bf16_f32 v73, v78, v79
	v_pk_mul_f32 v[48:49], v[48:49], v[108:109]
	v_cvt_pk_bf16_f32 v74, v74, v75
	v_cvt_pk_bf16_f32 v75, v82, v83
	global_store_dwordx4 v[80:81], v[72:75], off
	v_pk_mul_f32 v[38:39], v[38:39], v[102:103]
	v_pk_mul_f32 v[36:37], v[36:37], v[100:101]
	v_pk_mul_f32 v[72:73], v[66:67], v[98:99]
	v_pk_mul_f32 v[66:67], v[64:65], v[96:97]
	v_cvt_pk_bf16_f32 v64, v68, v69
	v_cvt_pk_bf16_f32 v65, v70, v71
	v_pk_mul_f32 v[32:33], v[32:33], v[108:109]
	v_cvt_pk_bf16_f32 v66, v66, v67
	v_cvt_pk_bf16_f32 v67, v72, v73
	global_store_dwordx4 v[80:81], v[64:67], off offset:256
	v_pk_mul_f32 v[22:23], v[22:23], v[102:103]
	v_pk_mul_f32 v[20:21], v[20:21], v[100:101]
	v_lshl_add_u64 v[64:65], v[166:167], 0, s[10:11]
	s_mov_b32 s10, 0x80000
	v_pk_mul_f32 v[66:67], v[58:59], v[106:107]
	v_pk_mul_f32 v[58:59], v[56:57], v[104:105]
	v_cvt_pk_bf16_f32 v56, v60, v61
	v_add_co_u32_e32 v60, vcc, s10, v166
	v_cvt_pk_bf16_f32 v57, v62, v63
	v_cvt_pk_bf16_f32 v58, v58, v59
	v_cvt_pk_bf16_f32 v59, v66, v67
	s_mov_b64 s[10:11], 0x90000
	s_nop 0
	v_addc_co_u32_e32 v61, vcc, 0, v167, vcc
	global_store_dwordx4 v[60:61], v[56:59], off
	v_pk_mul_f32 v[16:17], v[16:17], v[108:109]
	v_pk_mul_f32 v[6:7], v[6:7], v[102:103]
	v_pk_mul_f32 v[56:57], v[46:47], v[98:99]
	v_pk_mul_f32 v[46:47], v[44:45], v[96:97]
	v_cvt_pk_bf16_f32 v44, v52, v53
	v_cvt_pk_bf16_f32 v45, v54, v55
	v_pk_mul_f32 v[4:5], v[4:5], v[100:101]
	v_cvt_pk_bf16_f32 v46, v46, v47
	v_cvt_pk_bf16_f32 v47, v56, v57
	global_store_dwordx4 v[64:65], v[44:47], off offset:256
	s_nop 1
	v_lshl_add_u64 v[44:45], v[166:167], 0, s[10:11]
	v_pk_mul_f32 v[46:47], v[50:51], v[110:111]
	s_mov_b32 s10, 0x90000
	v_pk_mul_f32 v[50:51], v[42:43], v[106:107]
	v_pk_mul_f32 v[42:43], v[40:41], v[104:105]
	v_cvt_pk_bf16_f32 v40, v48, v49
	v_cvt_pk_bf16_f32 v41, v46, v47
	v_add_co_u32_e32 v46, vcc, s10, v166
	v_cvt_pk_bf16_f32 v42, v42, v43
	v_cvt_pk_bf16_f32 v43, v50, v51
	s_mov_b64 s[10:11], 0xa0000
	s_nop 0
	v_addc_co_u32_e32 v47, vcc, 0, v167, vcc
	global_store_dwordx4 v[46:47], v[40:43], off
	s_nop 1
	v_pk_mul_f32 v[40:41], v[30:31], v[98:99]
	v_pk_mul_f32 v[30:31], v[28:29], v[96:97]
	v_cvt_pk_bf16_f32 v28, v36, v37
	v_cvt_pk_bf16_f32 v29, v38, v39
	s_nop 0
	v_cvt_pk_bf16_f32 v30, v30, v31
	v_cvt_pk_bf16_f32 v31, v40, v41
	global_store_dwordx4 v[44:45], v[28:31], off offset:256
	s_nop 1
	v_lshl_add_u64 v[28:29], v[166:167], 0, s[10:11]
	v_pk_mul_f32 v[30:31], v[34:35], v[110:111]
	s_mov_b32 s10, 0xa0000
	v_pk_mul_f32 v[34:35], v[26:27], v[106:107]
	v_pk_mul_f32 v[26:27], v[24:25], v[104:105]
	v_cvt_pk_bf16_f32 v24, v32, v33
	v_cvt_pk_bf16_f32 v25, v30, v31
	v_add_co_u32_e32 v30, vcc, s10, v166
	v_cvt_pk_bf16_f32 v26, v26, v27
	v_cvt_pk_bf16_f32 v27, v34, v35
	s_mov_b64 s[10:11], 0xb0000
	s_nop 0
	v_addc_co_u32_e32 v31, vcc, 0, v167, vcc
	global_store_dwordx4 v[30:31], v[24:27], off
	s_nop 1
	v_pk_mul_f32 v[24:25], v[14:15], v[98:99]
	v_pk_mul_f32 v[14:15], v[12:13], v[96:97]
	v_cvt_pk_bf16_f32 v12, v20, v21
	v_cvt_pk_bf16_f32 v13, v22, v23
	s_nop 0
	v_cvt_pk_bf16_f32 v14, v14, v15
	v_cvt_pk_bf16_f32 v15, v24, v25
	global_store_dwordx4 v[28:29], v[12:15], off offset:256
	s_nop 1
	v_lshl_add_u64 v[12:13], v[166:167], 0, s[10:11]
	v_pk_mul_f32 v[14:15], v[18:19], v[110:111]
	s_mov_b32 s10, 0xb0000
	v_pk_mul_f32 v[18:19], v[10:11], v[106:107]
	v_pk_mul_f32 v[10:11], v[8:9], v[104:105]
	v_cvt_pk_bf16_f32 v8, v16, v17
	v_cvt_pk_bf16_f32 v9, v14, v15
	v_add_co_u32_e32 v14, vcc, s10, v166
	v_cvt_pk_bf16_f32 v10, v10, v11
	v_cvt_pk_bf16_f32 v11, v18, v19
	s_nop 1
	v_addc_co_u32_e32 v15, vcc, 0, v167, vcc
	global_store_dwordx4 v[14:15], v[8:11], off
	s_andn2_b64 vcc, exec, s[40:41]
	s_nop 0
	v_pk_mul_f32 v[8:9], v[2:3], v[98:99]
	v_pk_mul_f32 v[2:3], v[0:1], v[96:97]
	v_cvt_pk_bf16_f32 v0, v4, v5
	v_cvt_pk_bf16_f32 v1, v6, v7
	s_nop 0
	v_cvt_pk_bf16_f32 v2, v2, v3
	v_cvt_pk_bf16_f32 v3, v8, v9
	global_store_dwordx4 v[12:13], v[0:3], off offset:256
	s_cbranch_vccnz .LBB0_705
	s_andn2_b64 vcc, exec, s[42:43]
	s_cbranch_vccnz .LBB0_704
	s_barrier
	s_branch .LBB0_704

.LBB0_732:
	s_movk_i32 s31, 0x4100
	s_branch .LBB0_792
	s_waitcnt vmcnt(0)
	s_barrier
	s_and_saveexec_b64 s[0:1], s[56:57]
	s_movk_i32 s31, 0x4100
	s_cbranch_execz .LBB0_784
	v_readlane_b32 s4, v242, 0
	s_waitcnt vmcnt(0) expcnt(0) lgkmcnt(0)
	s_nop 0
	v_mov_b32_e32 v0, s4
	ds_read_b32 v2, v0
	v_readlane_b32 s4, v242, 1
	s_waitcnt lgkmcnt(0)
	v_cmp_ne_u32_e32 vcc, 0, v2
	v_mov_b32_e32 v0, s4
	ds_read_b32 v0, v0
	s_cbranch_vccnz .LBB0_748
	s_mov_b32 s4, 1
	s_branch .LBB0_736

.Lcf_entry:
	v_and_b32_e32 v23, 63, v175
	s_and_b32 s98, s2, 15
	s_lshl_b32 s98, s98, 9
	v_lshl_add_u32 v20, v23, 3, s98
	s_lshr_b32 s98, s98, 1
	v_lshl_add_u32 v21, v23, 2, s98
	v_lshlrev_b32_e32 v22, 3, v23
	v_add_u32_e32 v22, 0x11c80, v22
	s_and_b64 s[100:101], s[10:11], exec
	s_cselect_b32 s99, 0, 2
	s_lshr_b32 s100, s2, 4
	s_add_i32 s99, s99, s100
	s_and_b32 s99, s99, 15
	v_lshrrev_b32_e32 v23, 6, v175
	s_nop 1
	v_readfirstlane_b32 s98, v23
	s_nop 3
	s_cmp_eq_u32 s98, 1
	s_cbranch_scc1 .Lcf_var_1
	s_cmp_eq_u32 s98, 2
	s_cbranch_scc1 .Lcf_var_2
	s_cmp_eq_u32 s98, 3
	s_cbranch_scc1 .Lcf_var_3
	s_cmp_eq_u32 s98, 4
	s_cbranch_scc1 .Lcf_var_4
	s_cmp_eq_u32 s98, 5
	s_cbranch_scc1 .Lcf_var_5
	s_cmp_eq_u32 s98, 6
	s_cbranch_scc1 .Lcf_var_6
	s_cmp_eq_u32 s98, 7
	s_cbranch_scc1 .Lcf_var_7

.Lfe_start:
	v_lshl_or_b32 v166, s96, 8, v174
	v_ashrrev_i32_e32 v167, 31, v166
	v_lshl_add_u64 v[100:101], v[166:167], 2, s[44:45]
	global_load_dwordx4 v[104:107], v[100:101], off offset:16
	global_load_dwordx4 v[108:111], v[100:101], off
	global_load_dwordx4 v[96:99], v[100:101], off offset:528
	s_nop 0
	global_load_dwordx4 v[100:103], v[100:101], off offset:512
	v_lshl_add_u32 v170, s92, 8, v172
	v_ashrrev_i32_e32 v171, 31, v170
	s_add_u32 s100, s68, 0x3900000
	s_addc_u32 s101, s69, 0
	v_lshlrev_b64 v[168:169], 12, v[170:171]
	v_lshl_add_u64 v[168:169], s[100:101], 0, v[168:169]
	v_lshl_add_u64 v[168:169], v[166:167], 1, v[168:169]
	s_mov_b64 s[58:59], -1
	s_add_u32 s98, s68, 0x15e9c000
	s_addc_u32 s99, s69, 0
	v_lshl_add_u64 v[234:235], v[166:167], 2, s[98:99]
	global_load_dwordx4 v[190:193], v[234:235], off
	global_load_dwordx4 v[194:197], v[234:235], off offset:16
	s_add_u32 s98, s68, 0x15e98000
	s_addc_u32 s99, s69, 0
	v_lshl_add_u64 v[234:235], v[166:167], 2, s[98:99]
	global_load_dwordx4 v[198:201], v[234:235], off
	global_load_dwordx4 v[202:205], v[234:235], off offset:16
	v_mov_b32_e32 v166, v168
	v_mov_b32_e32 v167, v169
	global_load_dwordx4 v[206:209], v[166:167], off
	v_add_co_u32_e32 v166, vcc, 0x10000, v168
	s_nop 1
	v_addc_co_u32_e32 v167, vcc, 0, v169, vcc
	global_load_dwordx4 v[210:213], v[166:167], off
	v_add_co_u32_e32 v166, vcc, 0x20000, v168
	s_nop 1
	v_addc_co_u32_e32 v167, vcc, 0, v169, vcc
	global_load_dwordx4 v[214:217], v[166:167], off
	v_add_co_u32_e32 v166, vcc, 0x30000, v168
	s_nop 1
	v_addc_co_u32_e32 v167, vcc, 0, v169, vcc
	global_load_dwordx4 v[218:221], v[166:167], off
	v_add_co_u32_e32 v166, vcc, 0x80000, v168
	s_nop 1
	v_addc_co_u32_e32 v167, vcc, 0, v169, vcc
	global_load_dwordx4 v[222:225], v[166:167], off
	v_add_co_u32_e32 v166, vcc, 0x90000, v168
	s_nop 1
	v_addc_co_u32_e32 v167, vcc, 0, v169, vcc
	global_load_dwordx4 v[226:229], v[166:167], off
	v_add_co_u32_e32 v166, vcc, 0xa0000, v168
	s_nop 1
	v_addc_co_u32_e32 v167, vcc, 0, v169, vcc
	global_load_dwordx4 v[230:233], v[166:167], off
	s_waitcnt vmcnt(7)
	v_rcp_f32_e32 v198, v198
	v_rcp_f32_e32 v199, v199
	v_rcp_f32_e32 v200, v200
	v_rcp_f32_e32 v201, v201
	v_rcp_f32_e32 v202, v202
	v_rcp_f32_e32 v203, v203
	v_rcp_f32_e32 v204, v204
	v_rcp_f32_e32 v205, v205
	s_waitcnt vmcnt(11)
	s_waitcnt vmcnt(6)
	v_lshlrev_b32_e32 v234, 16, v206
	v_lshlrev_b32_e32 v236, 16, v207
	v_lshlrev_b32_e32 v238, 16, v208
	v_lshlrev_b32_e32 v240, 16, v209
	v_and_b32_e32 v235, 0xffff0000, v206
	v_and_b32_e32 v237, 0xffff0000, v207
	v_and_b32_e32 v239, 0xffff0000, v208
	v_and_b32_e32 v241, 0xffff0000, v209
	v_pk_mul_f32 v[234:235], v[234:235], v[198:199]
	v_pk_mul_f32 v[236:237], v[236:237], v[200:201]
	v_pk_mul_f32 v[238:239], v[238:239], v[202:203]
	v_pk_mul_f32 v[240:241], v[240:241], v[204:205]
	v_pk_fma_f32 v[140:141], v[140:141], v[108:109], v[234:235]
	v_pk_fma_f32 v[142:143], v[142:143], v[110:111], v[236:237]
	v_pk_fma_f32 v[136:137], v[136:137], v[104:105], v[238:239]
	v_pk_fma_f32 v[138:139], v[138:139], v[106:107], v[240:241]
	v_pk_mul_f32 v[246:247], v[140:141], v[140:141]
	v_pk_mul_f32 v[234:235], v[140:141], v[190:191]
	v_pk_mul_f32 v[236:237], v[142:143], v[192:193]
	v_pk_fma_f32 v[246:247], v[142:143], v[142:143], v[246:247]
	v_pk_mul_f32 v[238:239], v[136:137], v[194:195]
	v_pk_fma_f32 v[246:247], v[136:137], v[136:137], v[246:247]
	v_pk_mul_f32 v[240:241], v[138:139], v[196:197]
	v_pk_fma_f32 v[246:247], v[138:139], v[138:139], v[246:247]
	v_cvt_pk_bf16_f32 v136, v234, v235
	v_cvt_pk_bf16_f32 v137, v236, v237
	v_cvt_pk_bf16_f32 v138, v238, v239
	v_cvt_pk_bf16_f32 v139, v240, v241
	v_add_f32_e32 v140, v246, v247
	v_mov_b32_e32 v166, v168
	v_mov_b32_e32 v167, v169
	global_store_dwordx4 v[166:167], v[136:139], off
	v_add_co_u32_e32 v166, vcc, 0xb0000, v168
	s_nop 1
	v_addc_co_u32_e32 v167, vcc, 0, v169, vcc
	global_load_dwordx4 v[206:209], v[166:167], off
	s_waitcnt vmcnt(7)
	v_lshlrev_b32_e32 v234, 16, v210
	v_lshlrev_b32_e32 v236, 16, v211
	v_lshlrev_b32_e32 v238, 16, v212
	v_lshlrev_b32_e32 v240, 16, v213
	v_and_b32_e32 v235, 0xffff0000, v210
	v_and_b32_e32 v237, 0xffff0000, v211
	v_and_b32_e32 v239, 0xffff0000, v212
	v_and_b32_e32 v241, 0xffff0000, v213
	v_pk_mul_f32 v[234:235], v[234:235], v[198:199]
	v_pk_mul_f32 v[236:237], v[236:237], v[200:201]
	v_pk_mul_f32 v[238:239], v[238:239], v[202:203]
	v_pk_mul_f32 v[240:241], v[240:241], v[204:205]
	v_pk_fma_f32 v[124:125], v[124:125], v[108:109], v[234:235]
	v_pk_fma_f32 v[126:127], v[126:127], v[110:111], v[236:237]
	v_pk_fma_f32 v[120:121], v[120:121], v[104:105], v[238:239]
	v_pk_fma_f32 v[122:123], v[122:123], v[106:107], v[240:241]
	v_pk_mul_f32 v[246:247], v[124:125], v[124:125]
	v_pk_mul_f32 v[234:235], v[124:125], v[190:191]
	v_pk_mul_f32 v[236:237], v[126:127], v[192:193]
	v_pk_fma_f32 v[246:247], v[126:127], v[126:127], v[246:247]
	v_pk_mul_f32 v[238:239], v[120:121], v[194:195]
	v_pk_fma_f32 v[246:247], v[120:121], v[120:121], v[246:247]
	v_pk_mul_f32 v[240:241], v[122:123], v[196:197]
	v_pk_fma_f32 v[246:247], v[122:123], v[122:123], v[246:247]
	v_cvt_pk_bf16_f32 v120, v234, v235
	v_cvt_pk_bf16_f32 v121, v236, v237
	v_cvt_pk_bf16_f32 v122, v238, v239
	v_cvt_pk_bf16_f32 v123, v240, v241
	v_add_f32_e32 v124, v246, v247
	v_add_co_u32_e32 v166, vcc, 0x10000, v168
	s_nop 1
	v_addc_co_u32_e32 v167, vcc, 0, v169, vcc
	global_store_dwordx4 v[166:167], v[120:123], off
	s_waitcnt vmcnt(7)
	v_lshlrev_b32_e32 v234, 16, v214
	v_lshlrev_b32_e32 v236, 16, v215
	v_lshlrev_b32_e32 v238, 16, v216
	v_lshlrev_b32_e32 v240, 16, v217
	v_and_b32_e32 v235, 0xffff0000, v214
	v_and_b32_e32 v237, 0xffff0000, v215
	v_and_b32_e32 v239, 0xffff0000, v216
	v_and_b32_e32 v241, 0xffff0000, v217
	v_pk_mul_f32 v[234:235], v[234:235], v[198:199]
	v_pk_mul_f32 v[236:237], v[236:237], v[200:201]
	v_pk_mul_f32 v[238:239], v[238:239], v[202:203]
	v_pk_mul_f32 v[240:241], v[240:241], v[204:205]
	v_pk_fma_f32 v[92:93], v[92:93], v[108:109], v[234:235]
	v_pk_fma_f32 v[94:95], v[94:95], v[110:111], v[236:237]
	v_pk_fma_f32 v[88:89], v[88:89], v[104:105], v[238:239]
	v_pk_fma_f32 v[90:91], v[90:91], v[106:107], v[240:241]
	v_pk_mul_f32 v[246:247], v[92:93], v[92:93]
	v_pk_mul_f32 v[234:235], v[92:93], v[190:191]
	v_pk_mul_f32 v[236:237], v[94:95], v[192:193]
	v_pk_fma_f32 v[246:247], v[94:95], v[94:95], v[246:247]
	v_pk_mul_f32 v[238:239], v[88:89], v[194:195]
	v_pk_fma_f32 v[246:247], v[88:89], v[88:89], v[246:247]
	v_pk_mul_f32 v[240:241], v[90:91], v[196:197]
	v_pk_fma_f32 v[246:247], v[90:91], v[90:91], v[246:247]
	v_cvt_pk_bf16_f32 v88, v234, v235
	v_cvt_pk_bf16_f32 v89, v236, v237
	v_cvt_pk_bf16_f32 v90, v238, v239
	v_cvt_pk_bf16_f32 v91, v240, v241
	v_add_f32_e32 v92, v246, v247
	v_add_co_u32_e32 v166, vcc, 0x20000, v168
	s_nop 1
	v_addc_co_u32_e32 v167, vcc, 0, v169, vcc
	global_store_dwordx4 v[166:167], v[88:91], off
	s_waitcnt vmcnt(7)
	v_lshlrev_b32_e32 v234, 16, v218
	v_lshlrev_b32_e32 v236, 16, v219
	v_lshlrev_b32_e32 v238, 16, v220
	v_lshlrev_b32_e32 v240, 16, v221
	v_and_b32_e32 v235, 0xffff0000, v218
	v_and_b32_e32 v237, 0xffff0000, v219
	v_and_b32_e32 v239, 0xffff0000, v220
	v_and_b32_e32 v241, 0xffff0000, v221
	v_pk_mul_f32 v[234:235], v[234:235], v[198:199]
	v_pk_mul_f32 v[236:237], v[236:237], v[200:201]
	v_pk_mul_f32 v[238:239], v[238:239], v[202:203]
	v_pk_mul_f32 v[240:241], v[240:241], v[204:205]
	v_pk_fma_f32 v[76:77], v[76:77], v[108:109], v[234:235]
	v_pk_fma_f32 v[78:79], v[78:79], v[110:111], v[236:237]
	v_pk_fma_f32 v[72:73], v[72:73], v[104:105], v[238:239]
	v_pk_fma_f32 v[74:75], v[74:75], v[106:107], v[240:241]
	v_pk_mul_f32 v[246:247], v[76:77], v[76:77]
	v_pk_mul_f32 v[234:235], v[76:77], v[190:191]
	v_pk_mul_f32 v[236:237], v[78:79], v[192:193]
	v_pk_fma_f32 v[246:247], v[78:79], v[78:79], v[246:247]
	v_pk_mul_f32 v[238:239], v[72:73], v[194:195]
	v_pk_fma_f32 v[246:247], v[72:73], v[72:73], v[246:247]
	v_pk_mul_f32 v[240:241], v[74:75], v[196:197]
	v_pk_fma_f32 v[246:247], v[74:75], v[74:75], v[246:247]
	v_cvt_pk_bf16_f32 v72, v234, v235
	v_cvt_pk_bf16_f32 v73, v236, v237
	v_cvt_pk_bf16_f32 v74, v238, v239
	v_cvt_pk_bf16_f32 v75, v240, v241
	v_add_f32_e32 v76, v246, v247
	v_add_co_u32_e32 v166, vcc, 0x30000, v168
	s_nop 1
	v_addc_co_u32_e32 v167, vcc, 0, v169, vcc
	global_store_dwordx4 v[166:167], v[72:75], off
	s_waitcnt vmcnt(7)
	v_lshlrev_b32_e32 v234, 16, v222
	v_lshlrev_b32_e32 v236, 16, v223
	v_lshlrev_b32_e32 v238, 16, v224
	v_lshlrev_b32_e32 v240, 16, v225
	v_and_b32_e32 v235, 0xffff0000, v222
	v_and_b32_e32 v237, 0xffff0000, v223
	v_and_b32_e32 v239, 0xffff0000, v224
	v_and_b32_e32 v241, 0xffff0000, v225
	v_pk_mul_f32 v[234:235], v[234:235], v[198:199]
	v_pk_mul_f32 v[236:237], v[236:237], v[200:201]
	v_pk_mul_f32 v[238:239], v[238:239], v[202:203]
	v_pk_mul_f32 v[240:241], v[240:241], v[204:205]
	v_pk_fma_f32 v[60:61], v[60:61], v[108:109], v[234:235]
	v_pk_fma_f32 v[62:63], v[62:63], v[110:111], v[236:237]
	v_pk_fma_f32 v[56:57], v[56:57], v[104:105], v[238:239]
	v_pk_fma_f32 v[58:59], v[58:59], v[106:107], v[240:241]
	v_pk_mul_f32 v[246:247], v[60:61], v[60:61]
	v_pk_mul_f32 v[234:235], v[60:61], v[190:191]
	v_pk_mul_f32 v[236:237], v[62:63], v[192:193]
	v_pk_fma_f32 v[246:247], v[62:63], v[62:63], v[246:247]
	v_pk_mul_f32 v[238:239], v[56:57], v[194:195]
	v_pk_fma_f32 v[246:247], v[56:57], v[56:57], v[246:247]
	v_pk_mul_f32 v[240:241], v[58:59], v[196:197]
	v_pk_fma_f32 v[246:247], v[58:59], v[58:59], v[246:247]
	v_cvt_pk_bf16_f32 v56, v234, v235
	v_cvt_pk_bf16_f32 v57, v236, v237
	v_cvt_pk_bf16_f32 v58, v238, v239
	v_cvt_pk_bf16_f32 v59, v240, v241
	v_add_f32_e32 v60, v246, v247
	v_add_co_u32_e32 v166, vcc, 0x80000, v168
	s_nop 1
	v_addc_co_u32_e32 v167, vcc, 0, v169, vcc
	global_store_dwordx4 v[166:167], v[56:59], off
	s_waitcnt vmcnt(7)
	v_lshlrev_b32_e32 v234, 16, v226
	v_lshlrev_b32_e32 v236, 16, v227
	v_lshlrev_b32_e32 v238, 16, v228
	v_lshlrev_b32_e32 v240, 16, v229
	v_and_b32_e32 v235, 0xffff0000, v226
	v_and_b32_e32 v237, 0xffff0000, v227
	v_and_b32_e32 v239, 0xffff0000, v228
	v_and_b32_e32 v241, 0xffff0000, v229
	v_pk_mul_f32 v[234:235], v[234:235], v[198:199]
	v_pk_mul_f32 v[236:237], v[236:237], v[200:201]
	v_pk_mul_f32 v[238:239], v[238:239], v[202:203]
	v_pk_mul_f32 v[240:241], v[240:241], v[204:205]
	v_pk_fma_f32 v[48:49], v[48:49], v[108:109], v[234:235]
	v_pk_fma_f32 v[50:51], v[50:51], v[110:111], v[236:237]
	v_pk_fma_f32 v[40:41], v[40:41], v[104:105], v[238:239]
	v_pk_fma_f32 v[42:43], v[42:43], v[106:107], v[240:241]
	v_pk_mul_f32 v[246:247], v[48:49], v[48:49]
	v_pk_mul_f32 v[234:235], v[48:49], v[190:191]
	v_pk_mul_f32 v[236:237], v[50:51], v[192:193]
	v_pk_fma_f32 v[246:247], v[50:51], v[50:51], v[246:247]
	v_pk_mul_f32 v[238:239], v[40:41], v[194:195]
	v_pk_fma_f32 v[246:247], v[40:41], v[40:41], v[246:247]
	v_pk_mul_f32 v[240:241], v[42:43], v[196:197]
	v_pk_fma_f32 v[246:247], v[42:43], v[42:43], v[246:247]
	v_cvt_pk_bf16_f32 v40, v234, v235
	v_cvt_pk_bf16_f32 v41, v236, v237
	v_cvt_pk_bf16_f32 v42, v238, v239
	v_cvt_pk_bf16_f32 v43, v240, v241
	v_add_f32_e32 v48, v246, v247
	v_add_co_u32_e32 v166, vcc, 0x90000, v168
	s_nop 1
	v_addc_co_u32_e32 v167, vcc, 0, v169, vcc
	global_store_dwordx4 v[166:167], v[40:43], off
	s_waitcnt vmcnt(7)
	v_lshlrev_b32_e32 v234, 16, v230
	v_lshlrev_b32_e32 v236, 16, v231
	v_lshlrev_b32_e32 v238, 16, v232
	v_lshlrev_b32_e32 v240, 16, v233
	v_and_b32_e32 v235, 0xffff0000, v230
	v_and_b32_e32 v237, 0xffff0000, v231
	v_and_b32_e32 v239, 0xffff0000, v232
	v_and_b32_e32 v241, 0xffff0000, v233
	v_pk_mul_f32 v[234:235], v[234:235], v[198:199]
	v_pk_mul_f32 v[236:237], v[236:237], v[200:201]
	v_pk_mul_f32 v[238:239], v[238:239], v[202:203]
	v_pk_mul_f32 v[240:241], v[240:241], v[204:205]
	v_pk_fma_f32 v[32:33], v[32:33], v[108:109], v[234:235]
	v_pk_fma_f32 v[34:35], v[34:35], v[110:111], v[236:237]
	v_pk_fma_f32 v[24:25], v[24:25], v[104:105], v[238:239]
	v_pk_fma_f32 v[26:27], v[26:27], v[106:107], v[240:241]
	v_pk_mul_f32 v[246:247], v[32:33], v[32:33]
	v_pk_mul_f32 v[234:235], v[32:33], v[190:191]
	v_pk_mul_f32 v[236:237], v[34:35], v[192:193]
	v_pk_fma_f32 v[246:247], v[34:35], v[34:35], v[246:247]
	v_pk_mul_f32 v[238:239], v[24:25], v[194:195]
	v_pk_fma_f32 v[246:247], v[24:25], v[24:25], v[246:247]
	v_pk_mul_f32 v[240:241], v[26:27], v[196:197]
	v_pk_fma_f32 v[246:247], v[26:27], v[26:27], v[246:247]
	v_cvt_pk_bf16_f32 v24, v234, v235
	v_cvt_pk_bf16_f32 v25, v236, v237
	v_cvt_pk_bf16_f32 v26, v238, v239
	v_cvt_pk_bf16_f32 v27, v240, v241
	v_add_f32_e32 v32, v246, v247
	v_add_co_u32_e32 v166, vcc, 0xa0000, v168
	s_nop 1
	v_addc_co_u32_e32 v167, vcc, 0, v169, vcc
	global_store_dwordx4 v[166:167], v[24:27], off
	s_waitcnt vmcnt(6)
	v_lshlrev_b32_e32 v234, 16, v206
	v_lshlrev_b32_e32 v236, 16, v207
	v_lshlrev_b32_e32 v238, 16, v208
	v_lshlrev_b32_e32 v240, 16, v209
	v_and_b32_e32 v235, 0xffff0000, v206
	v_and_b32_e32 v237, 0xffff0000, v207
	v_and_b32_e32 v239, 0xffff0000, v208
	v_and_b32_e32 v241, 0xffff0000, v209
	v_pk_mul_f32 v[234:235], v[234:235], v[198:199]
	v_pk_mul_f32 v[236:237], v[236:237], v[200:201]
	v_pk_mul_f32 v[238:239], v[238:239], v[202:203]
	v_pk_mul_f32 v[240:241], v[240:241], v[204:205]
	v_pk_fma_f32 v[16:17], v[16:17], v[108:109], v[234:235]
	v_pk_fma_f32 v[18:19], v[18:19], v[110:111], v[236:237]
	v_pk_fma_f32 v[8:9], v[8:9], v[104:105], v[238:239]
	v_pk_fma_f32 v[10:11], v[10:11], v[106:107], v[240:241]
	v_pk_mul_f32 v[246:247], v[16:17], v[16:17]
	v_pk_mul_f32 v[234:235], v[16:17], v[190:191]
	v_pk_mul_f32 v[236:237], v[18:19], v[192:193]
	v_pk_fma_f32 v[246:247], v[18:19], v[18:19], v[246:247]
	v_pk_mul_f32 v[238:239], v[8:9], v[194:195]
	v_pk_fma_f32 v[246:247], v[8:9], v[8:9], v[246:247]
	v_pk_mul_f32 v[240:241], v[10:11], v[196:197]
	v_pk_fma_f32 v[246:247], v[10:11], v[10:11], v[246:247]
	v_cvt_pk_bf16_f32 v8, v234, v235
	v_cvt_pk_bf16_f32 v9, v236, v237
	v_cvt_pk_bf16_f32 v10, v238, v239
	v_cvt_pk_bf16_f32 v11, v240, v241
	v_add_f32_e32 v16, v246, v247
	v_add_co_u32_e32 v166, vcc, 0xb0000, v168
	s_nop 1
	v_addc_co_u32_e32 v167, vcc, 0, v169, vcc
	global_store_dwordx4 v[166:167], v[8:11], off
	v_lshl_or_b32 v166, s96, 8, v174
	v_ashrrev_i32_e32 v167, 31, v166
	s_add_u32 s98, s68, 0x15e9c200
	s_addc_u32 s99, s69, 0
	v_lshl_add_u64 v[234:235], v[166:167], 2, s[98:99]
	global_load_dwordx4 v[190:193], v[234:235], off
	global_load_dwordx4 v[194:197], v[234:235], off offset:16
	s_add_u32 s98, s68, 0x15e98200
	s_addc_u32 s99, s69, 0
	v_lshl_add_u64 v[234:235], v[166:167], 2, s[98:99]
	global_load_dwordx4 v[198:201], v[234:235], off
	global_load_dwordx4 v[202:205], v[234:235], off offset:16
	v_mov_b32_e32 v166, v168
	v_mov_b32_e32 v167, v169
	global_load_dwordx4 v[206:209], v[166:167], off offset:256
	v_add_co_u32_e32 v166, vcc, 0x10000, v168
	s_nop 1
	v_addc_co_u32_e32 v167, vcc, 0, v169, vcc
	global_load_dwordx4 v[210:213], v[166:167], off offset:256
	v_add_co_u32_e32 v166, vcc, 0x20000, v168
	s_nop 1
	v_addc_co_u32_e32 v167, vcc, 0, v169, vcc
	global_load_dwordx4 v[214:217], v[166:167], off offset:256
	v_add_co_u32_e32 v166, vcc, 0x30000, v168
	s_nop 1
	v_addc_co_u32_e32 v167, vcc, 0, v169, vcc
	global_load_dwordx4 v[218:221], v[166:167], off offset:256
	v_add_co_u32_e32 v166, vcc, 0x80000, v168
	s_nop 1
	v_addc_co_u32_e32 v167, vcc, 0, v169, vcc
	global_load_dwordx4 v[222:225], v[166:167], off offset:256
	v_add_co_u32_e32 v166, vcc, 0x90000, v168
	s_nop 1
	v_addc_co_u32_e32 v167, vcc, 0, v169, vcc
	global_load_dwordx4 v[226:229], v[166:167], off offset:256
	v_add_co_u32_e32 v166, vcc, 0xa0000, v168
	s_nop 1
	v_addc_co_u32_e32 v167, vcc, 0, v169, vcc
	global_load_dwordx4 v[230:233], v[166:167], off offset:256
	s_waitcnt vmcnt(7)
	v_rcp_f32_e32 v198, v198
	v_rcp_f32_e32 v199, v199
	v_rcp_f32_e32 v200, v200
	v_rcp_f32_e32 v201, v201
	v_rcp_f32_e32 v202, v202
	v_rcp_f32_e32 v203, v203
	v_rcp_f32_e32 v204, v204
	v_rcp_f32_e32 v205, v205
	s_waitcnt vmcnt(6)
	v_lshlrev_b32_e32 v234, 16, v206
	v_lshlrev_b32_e32 v236, 16, v207
	v_lshlrev_b32_e32 v238, 16, v208
	v_lshlrev_b32_e32 v240, 16, v209
	v_and_b32_e32 v235, 0xffff0000, v206
	v_and_b32_e32 v237, 0xffff0000, v207
	v_and_b32_e32 v239, 0xffff0000, v208
	v_and_b32_e32 v241, 0xffff0000, v209
	v_pk_mul_f32 v[234:235], v[234:235], v[198:199]
	v_pk_mul_f32 v[236:237], v[236:237], v[200:201]
	v_pk_mul_f32 v[238:239], v[238:239], v[202:203]
	v_pk_mul_f32 v[240:241], v[240:241], v[204:205]
	v_pk_fma_f32 v[132:133], v[132:133], v[100:101], v[234:235]
	v_pk_fma_f32 v[134:135], v[134:135], v[102:103], v[236:237]
	v_pk_fma_f32 v[128:129], v[128:129], v[96:97], v[238:239]
	v_pk_fma_f32 v[130:131], v[130:131], v[98:99], v[240:241]
	v_pk_mul_f32 v[246:247], v[132:133], v[132:133]
	v_pk_mul_f32 v[234:235], v[132:133], v[190:191]
	v_pk_mul_f32 v[236:237], v[134:135], v[192:193]
	v_pk_fma_f32 v[246:247], v[134:135], v[134:135], v[246:247]
	v_pk_mul_f32 v[238:239], v[128:129], v[194:195]
	v_pk_fma_f32 v[246:247], v[128:129], v[128:129], v[246:247]
	v_pk_mul_f32 v[240:241], v[130:131], v[196:197]
	v_pk_fma_f32 v[246:247], v[130:131], v[130:131], v[246:247]
	v_cvt_pk_bf16_f32 v128, v234, v235
	v_cvt_pk_bf16_f32 v129, v236, v237
	v_cvt_pk_bf16_f32 v130, v238, v239
	v_cvt_pk_bf16_f32 v131, v240, v241
	v_add_f32_e32 v246, v246, v247
	s_nop 0
	v_add_f32_e32 v140, v140, v246
	v_mov_b32_e32 v166, v168
	v_mov_b32_e32 v167, v169
	global_store_dwordx4 v[166:167], v[128:131], off offset:256
	v_add_co_u32_e32 v166, vcc, 0xb0000, v168
	s_nop 1
	v_addc_co_u32_e32 v167, vcc, 0, v169, vcc
	global_load_dwordx4 v[206:209], v[166:167], off offset:256
	s_waitcnt vmcnt(7)
	v_lshlrev_b32_e32 v234, 16, v210
	v_lshlrev_b32_e32 v236, 16, v211
	v_lshlrev_b32_e32 v238, 16, v212
	v_lshlrev_b32_e32 v240, 16, v213
	v_and_b32_e32 v235, 0xffff0000, v210
	v_and_b32_e32 v237, 0xffff0000, v211
	v_and_b32_e32 v239, 0xffff0000, v212
	v_and_b32_e32 v241, 0xffff0000, v213
	v_pk_mul_f32 v[234:235], v[234:235], v[198:199]
	v_pk_mul_f32 v[236:237], v[236:237], v[200:201]
	v_pk_mul_f32 v[238:239], v[238:239], v[202:203]
	v_pk_mul_f32 v[240:241], v[240:241], v[204:205]
	v_pk_fma_f32 v[116:117], v[116:117], v[100:101], v[234:235]
	v_pk_fma_f32 v[118:119], v[118:119], v[102:103], v[236:237]
	v_pk_fma_f32 v[112:113], v[112:113], v[96:97], v[238:239]
	v_pk_fma_f32 v[114:115], v[114:115], v[98:99], v[240:241]
	v_pk_mul_f32 v[246:247], v[116:117], v[116:117]
	v_pk_mul_f32 v[234:235], v[116:117], v[190:191]
	v_pk_mul_f32 v[236:237], v[118:119], v[192:193]
	v_pk_fma_f32 v[246:247], v[118:119], v[118:119], v[246:247]
	v_pk_mul_f32 v[238:239], v[112:113], v[194:195]
	v_pk_fma_f32 v[246:247], v[112:113], v[112:113], v[246:247]
	v_pk_mul_f32 v[240:241], v[114:115], v[196:197]
	v_pk_fma_f32 v[246:247], v[114:115], v[114:115], v[246:247]
	v_cvt_pk_bf16_f32 v112, v234, v235
	v_cvt_pk_bf16_f32 v113, v236, v237
	v_cvt_pk_bf16_f32 v114, v238, v239
	v_cvt_pk_bf16_f32 v115, v240, v241
	v_add_f32_e32 v246, v246, v247
	s_nop 0
	v_add_f32_e32 v124, v124, v246
	v_add_co_u32_e32 v166, vcc, 0x10000, v168
	s_nop 1
	v_addc_co_u32_e32 v167, vcc, 0, v169, vcc
	global_store_dwordx4 v[166:167], v[112:115], off offset:256
	s_waitcnt vmcnt(7)
	v_lshlrev_b32_e32 v234, 16, v214
	v_lshlrev_b32_e32 v236, 16, v215
	v_lshlrev_b32_e32 v238, 16, v216
	v_lshlrev_b32_e32 v240, 16, v217
	v_and_b32_e32 v235, 0xffff0000, v214
	v_and_b32_e32 v237, 0xffff0000, v215
	v_and_b32_e32 v239, 0xffff0000, v216
	v_and_b32_e32 v241, 0xffff0000, v217
	v_pk_mul_f32 v[234:235], v[234:235], v[198:199]
	v_pk_mul_f32 v[236:237], v[236:237], v[200:201]
	v_pk_mul_f32 v[238:239], v[238:239], v[202:203]
	v_pk_mul_f32 v[240:241], v[240:241], v[204:205]
	v_pk_fma_f32 v[84:85], v[84:85], v[100:101], v[234:235]
	v_pk_fma_f32 v[86:87], v[86:87], v[102:103], v[236:237]
	v_pk_fma_f32 v[80:81], v[80:81], v[96:97], v[238:239]
	v_pk_fma_f32 v[82:83], v[82:83], v[98:99], v[240:241]
	v_pk_mul_f32 v[246:247], v[84:85], v[84:85]
	v_pk_mul_f32 v[234:235], v[84:85], v[190:191]
	v_pk_mul_f32 v[236:237], v[86:87], v[192:193]
	v_pk_fma_f32 v[246:247], v[86:87], v[86:87], v[246:247]
	v_pk_mul_f32 v[238:239], v[80:81], v[194:195]
	v_pk_fma_f32 v[246:247], v[80:81], v[80:81], v[246:247]
	v_pk_mul_f32 v[240:241], v[82:83], v[196:197]
	v_pk_fma_f32 v[246:247], v[82:83], v[82:83], v[246:247]
	v_cvt_pk_bf16_f32 v80, v234, v235
	v_cvt_pk_bf16_f32 v81, v236, v237
	v_cvt_pk_bf16_f32 v82, v238, v239
	v_cvt_pk_bf16_f32 v83, v240, v241
	v_add_f32_e32 v246, v246, v247
	s_nop 0
	v_add_f32_e32 v92, v92, v246
	v_add_co_u32_e32 v166, vcc, 0x20000, v168
	s_nop 1
	v_addc_co_u32_e32 v167, vcc, 0, v169, vcc
	global_store_dwordx4 v[166:167], v[80:83], off offset:256
	s_waitcnt vmcnt(7)
	v_lshlrev_b32_e32 v234, 16, v218
	v_lshlrev_b32_e32 v236, 16, v219
	v_lshlrev_b32_e32 v238, 16, v220
	v_lshlrev_b32_e32 v240, 16, v221
	v_and_b32_e32 v235, 0xffff0000, v218
	v_and_b32_e32 v237, 0xffff0000, v219
	v_and_b32_e32 v239, 0xffff0000, v220
	v_and_b32_e32 v241, 0xffff0000, v221
	v_pk_mul_f32 v[234:235], v[234:235], v[198:199]
	v_pk_mul_f32 v[236:237], v[236:237], v[200:201]
	v_pk_mul_f32 v[238:239], v[238:239], v[202:203]
	v_pk_mul_f32 v[240:241], v[240:241], v[204:205]
	v_pk_fma_f32 v[68:69], v[68:69], v[100:101], v[234:235]
	v_pk_fma_f32 v[70:71], v[70:71], v[102:103], v[236:237]
	v_pk_fma_f32 v[64:65], v[64:65], v[96:97], v[238:239]
	v_pk_fma_f32 v[66:67], v[66:67], v[98:99], v[240:241]
	v_pk_mul_f32 v[246:247], v[68:69], v[68:69]
	v_pk_mul_f32 v[234:235], v[68:69], v[190:191]
	v_pk_mul_f32 v[236:237], v[70:71], v[192:193]
	v_pk_fma_f32 v[246:247], v[70:71], v[70:71], v[246:247]
	v_pk_mul_f32 v[238:239], v[64:65], v[194:195]
	v_pk_fma_f32 v[246:247], v[64:65], v[64:65], v[246:247]
	v_pk_mul_f32 v[240:241], v[66:67], v[196:197]
	v_pk_fma_f32 v[246:247], v[66:67], v[66:67], v[246:247]
	v_cvt_pk_bf16_f32 v64, v234, v235
	v_cvt_pk_bf16_f32 v65, v236, v237
	v_cvt_pk_bf16_f32 v66, v238, v239
	v_cvt_pk_bf16_f32 v67, v240, v241
	v_add_f32_e32 v246, v246, v247
	s_nop 0
	v_add_f32_e32 v76, v76, v246
	v_add_co_u32_e32 v166, vcc, 0x30000, v168
	s_nop 1
	v_addc_co_u32_e32 v167, vcc, 0, v169, vcc
	global_store_dwordx4 v[166:167], v[64:67], off offset:256
	s_waitcnt vmcnt(7)
	v_lshlrev_b32_e32 v234, 16, v222
	v_lshlrev_b32_e32 v236, 16, v223
	v_lshlrev_b32_e32 v238, 16, v224
	v_lshlrev_b32_e32 v240, 16, v225
	v_and_b32_e32 v235, 0xffff0000, v222
	v_and_b32_e32 v237, 0xffff0000, v223
	v_and_b32_e32 v239, 0xffff0000, v224
	v_and_b32_e32 v241, 0xffff0000, v225
	v_pk_mul_f32 v[234:235], v[234:235], v[198:199]
	v_pk_mul_f32 v[236:237], v[236:237], v[200:201]
	v_pk_mul_f32 v[238:239], v[238:239], v[202:203]
	v_pk_mul_f32 v[240:241], v[240:241], v[204:205]
	v_pk_fma_f32 v[52:53], v[52:53], v[100:101], v[234:235]
	v_pk_fma_f32 v[54:55], v[54:55], v[102:103], v[236:237]
	v_pk_fma_f32 v[44:45], v[44:45], v[96:97], v[238:239]
	v_pk_fma_f32 v[46:47], v[46:47], v[98:99], v[240:241]
	v_pk_mul_f32 v[246:247], v[52:53], v[52:53]
	v_pk_mul_f32 v[234:235], v[52:53], v[190:191]
	v_pk_mul_f32 v[236:237], v[54:55], v[192:193]
	v_pk_fma_f32 v[246:247], v[54:55], v[54:55], v[246:247]
	v_pk_mul_f32 v[238:239], v[44:45], v[194:195]
	v_pk_fma_f32 v[246:247], v[44:45], v[44:45], v[246:247]
	v_pk_mul_f32 v[240:241], v[46:47], v[196:197]
	v_pk_fma_f32 v[246:247], v[46:47], v[46:47], v[246:247]
	v_cvt_pk_bf16_f32 v44, v234, v235
	v_cvt_pk_bf16_f32 v45, v236, v237
	v_cvt_pk_bf16_f32 v46, v238, v239
	v_cvt_pk_bf16_f32 v47, v240, v241
	v_add_f32_e32 v246, v246, v247
	s_nop 0
	v_add_f32_e32 v60, v60, v246
	v_add_co_u32_e32 v166, vcc, 0x80000, v168
	s_nop 1
	v_addc_co_u32_e32 v167, vcc, 0, v169, vcc
	global_store_dwordx4 v[166:167], v[44:47], off offset:256
	s_waitcnt vmcnt(7)
	v_lshlrev_b32_e32 v234, 16, v226
	v_lshlrev_b32_e32 v236, 16, v227
	v_lshlrev_b32_e32 v238, 16, v228
	v_lshlrev_b32_e32 v240, 16, v229
	v_and_b32_e32 v235, 0xffff0000, v226
	v_and_b32_e32 v237, 0xffff0000, v227
	v_and_b32_e32 v239, 0xffff0000, v228
	v_and_b32_e32 v241, 0xffff0000, v229
	v_pk_mul_f32 v[234:235], v[234:235], v[198:199]
	v_pk_mul_f32 v[236:237], v[236:237], v[200:201]
	v_pk_mul_f32 v[238:239], v[238:239], v[202:203]
	v_pk_mul_f32 v[240:241], v[240:241], v[204:205]
	v_pk_fma_f32 v[36:37], v[36:37], v[100:101], v[234:235]
	v_pk_fma_f32 v[38:39], v[38:39], v[102:103], v[236:237]
	v_pk_fma_f32 v[28:29], v[28:29], v[96:97], v[238:239]
	v_pk_fma_f32 v[30:31], v[30:31], v[98:99], v[240:241]
	v_pk_mul_f32 v[246:247], v[36:37], v[36:37]
	v_pk_mul_f32 v[234:235], v[36:37], v[190:191]
	v_pk_mul_f32 v[236:237], v[38:39], v[192:193]
	v_pk_fma_f32 v[246:247], v[38:39], v[38:39], v[246:247]
	v_pk_mul_f32 v[238:239], v[28:29], v[194:195]
	v_pk_fma_f32 v[246:247], v[28:29], v[28:29], v[246:247]
	v_pk_mul_f32 v[240:241], v[30:31], v[196:197]
	v_pk_fma_f32 v[246:247], v[30:31], v[30:31], v[246:247]
	v_cvt_pk_bf16_f32 v28, v234, v235
	v_cvt_pk_bf16_f32 v29, v236, v237
	v_cvt_pk_bf16_f32 v30, v238, v239
	v_cvt_pk_bf16_f32 v31, v240, v241
	v_add_f32_e32 v246, v246, v247
	s_nop 0
	v_add_f32_e32 v48, v48, v246
	v_add_co_u32_e32 v166, vcc, 0x90000, v168
	s_nop 1
	v_addc_co_u32_e32 v167, vcc, 0, v169, vcc
	global_store_dwordx4 v[166:167], v[28:31], off offset:256
	s_waitcnt vmcnt(7)
	v_lshlrev_b32_e32 v234, 16, v230
	v_lshlrev_b32_e32 v236, 16, v231
	v_lshlrev_b32_e32 v238, 16, v232
	v_lshlrev_b32_e32 v240, 16, v233
	v_and_b32_e32 v235, 0xffff0000, v230
	v_and_b32_e32 v237, 0xffff0000, v231
	v_and_b32_e32 v239, 0xffff0000, v232
	v_and_b32_e32 v241, 0xffff0000, v233
	v_pk_mul_f32 v[234:235], v[234:235], v[198:199]
	v_pk_mul_f32 v[236:237], v[236:237], v[200:201]
	v_pk_mul_f32 v[238:239], v[238:239], v[202:203]
	v_pk_mul_f32 v[240:241], v[240:241], v[204:205]
	v_pk_fma_f32 v[20:21], v[20:21], v[100:101], v[234:235]
	v_pk_fma_f32 v[22:23], v[22:23], v[102:103], v[236:237]
	v_pk_fma_f32 v[12:13], v[12:13], v[96:97], v[238:239]
	v_pk_fma_f32 v[14:15], v[14:15], v[98:99], v[240:241]
	v_pk_mul_f32 v[246:247], v[20:21], v[20:21]
	v_pk_mul_f32 v[234:235], v[20:21], v[190:191]
	v_pk_mul_f32 v[236:237], v[22:23], v[192:193]
	v_pk_fma_f32 v[246:247], v[22:23], v[22:23], v[246:247]
	v_pk_mul_f32 v[238:239], v[12:13], v[194:195]
	v_pk_fma_f32 v[246:247], v[12:13], v[12:13], v[246:247]
	v_pk_mul_f32 v[240:241], v[14:15], v[196:197]
	v_pk_fma_f32 v[246:247], v[14:15], v[14:15], v[246:247]
	v_cvt_pk_bf16_f32 v12, v234, v235
	v_cvt_pk_bf16_f32 v13, v236, v237
	v_cvt_pk_bf16_f32 v14, v238, v239
	v_cvt_pk_bf16_f32 v15, v240, v241
	v_add_f32_e32 v246, v246, v247
	s_nop 0
	v_add_f32_e32 v32, v32, v246
	v_add_co_u32_e32 v166, vcc, 0xa0000, v168
	s_nop 1
	v_addc_co_u32_e32 v167, vcc, 0, v169, vcc
	global_store_dwordx4 v[166:167], v[12:15], off offset:256
	s_waitcnt vmcnt(6)
	v_lshlrev_b32_e32 v234, 16, v206
	v_lshlrev_b32_e32 v236, 16, v207
	v_lshlrev_b32_e32 v238, 16, v208
	v_lshlrev_b32_e32 v240, 16, v209
	v_and_b32_e32 v235, 0xffff0000, v206
	v_and_b32_e32 v237, 0xffff0000, v207
	v_and_b32_e32 v239, 0xffff0000, v208
	v_and_b32_e32 v241, 0xffff0000, v209
	v_pk_mul_f32 v[234:235], v[234:235], v[198:199]
	v_pk_mul_f32 v[236:237], v[236:237], v[200:201]
	v_pk_mul_f32 v[238:239], v[238:239], v[202:203]
	v_pk_mul_f32 v[240:241], v[240:241], v[204:205]
	v_pk_fma_f32 v[4:5], v[4:5], v[100:101], v[234:235]
	v_pk_fma_f32 v[6:7], v[6:7], v[102:103], v[236:237]
	v_pk_fma_f32 v[0:1], v[0:1], v[96:97], v[238:239]
	v_pk_fma_f32 v[2:3], v[2:3], v[98:99], v[240:241]
	v_pk_mul_f32 v[246:247], v[4:5], v[4:5]
	v_pk_mul_f32 v[234:235], v[4:5], v[190:191]
	v_pk_mul_f32 v[236:237], v[6:7], v[192:193]
	v_pk_fma_f32 v[246:247], v[6:7], v[6:7], v[246:247]
	v_pk_mul_f32 v[238:239], v[0:1], v[194:195]
	v_pk_fma_f32 v[246:247], v[0:1], v[0:1], v[246:247]
	v_pk_mul_f32 v[240:241], v[2:3], v[196:197]
	v_pk_fma_f32 v[246:247], v[2:3], v[2:3], v[246:247]
	v_cvt_pk_bf16_f32 v0, v234, v235
	v_cvt_pk_bf16_f32 v1, v236, v237
	v_cvt_pk_bf16_f32 v2, v238, v239
	v_cvt_pk_bf16_f32 v3, v240, v241
	v_add_f32_e32 v246, v246, v247
	s_nop 0
	v_add_f32_e32 v16, v16, v246
	v_add_co_u32_e32 v166, vcc, 0xb0000, v168
	s_nop 1
	v_addc_co_u32_e32 v167, vcc, 0, v169, vcc
	global_store_dwordx4 v[166:167], v[0:3], off offset:256
	v_and_b32_e32 v234, 63, v175
	v_xor_b32_e32 v235, 16, v234
	v_xor_b32_e32 v236, 32, v234
	v_lshlrev_b32_e32 v235, 2, v235
	v_lshlrev_b32_e32 v236, 2, v236
	ds_bpermute_b32 v206, v235, v140
	ds_bpermute_b32 v207, v235, v124
	ds_bpermute_b32 v208, v235, v92
	ds_bpermute_b32 v209, v235, v76
	ds_bpermute_b32 v210, v235, v60
	ds_bpermute_b32 v211, v235, v48
	ds_bpermute_b32 v212, v235, v32
	ds_bpermute_b32 v213, v235, v16
	s_waitcnt lgkmcnt(0)
	v_add_f32_e32 v140, v140, v206
	v_add_f32_e32 v124, v124, v207
	v_add_f32_e32 v92, v92, v208
	v_add_f32_e32 v76, v76, v209
	v_add_f32_e32 v60, v60, v210
	v_add_f32_e32 v48, v48, v211
	v_add_f32_e32 v32, v32, v212
	v_add_f32_e32 v16, v16, v213
	ds_bpermute_b32 v206, v236, v140
	ds_bpermute_b32 v207, v236, v124
	ds_bpermute_b32 v208, v236, v92
	ds_bpermute_b32 v209, v236, v76
	ds_bpermute_b32 v210, v236, v60
	ds_bpermute_b32 v211, v236, v48
	ds_bpermute_b32 v212, v236, v32
	ds_bpermute_b32 v213, v236, v16
	s_waitcnt lgkmcnt(0)
	v_add_f32_e32 v140, v140, v206
	v_add_f32_e32 v124, v124, v207
	v_add_f32_e32 v92, v92, v208
	v_add_f32_e32 v76, v76, v209
	v_add_f32_e32 v60, v60, v210
	v_add_f32_e32 v48, v48, v211
	v_add_f32_e32 v32, v32, v212
	v_add_f32_e32 v16, v16, v213
	s_add_u32 s98, s68, 0x15ec4800
	s_addc_u32 s99, s69, 0
	v_cmp_gt_u32_e32 vcc, 16, v234
	s_and_saveexec_b64 s[100:101], vcc
	v_add_u32_e32 v214, 0, v170
	v_lshlrev_b32_e32 v214, 2, v214
	v_add_u32_e32 v215, 16, v170
	v_lshlrev_b32_e32 v215, 2, v215
	v_add_u32_e32 v216, 32, v170
	v_lshlrev_b32_e32 v216, 2, v216
	v_add_u32_e32 v217, 48, v170
	v_lshlrev_b32_e32 v217, 2, v217
	v_add_u32_e32 v218, 128, v170
	v_lshlrev_b32_e32 v218, 2, v218
	v_add_u32_e32 v219, 144, v170
	v_lshlrev_b32_e32 v219, 2, v219
	v_add_u32_e32 v220, 160, v170
	v_lshlrev_b32_e32 v220, 2, v220
	v_add_u32_e32 v221, 176, v170
	v_lshlrev_b32_e32 v221, 2, v221
	global_atomic_add_f32 v214, v140, s[98:99]
	global_atomic_add_f32 v215, v124, s[98:99]
	global_atomic_add_f32 v216, v92, s[98:99]
	global_atomic_add_f32 v217, v76, s[98:99]
	global_atomic_add_f32 v218, v60, s[98:99]
	global_atomic_add_f32 v219, v48, s[98:99]
	global_atomic_add_f32 v220, v32, s[98:99]
	global_atomic_add_f32 v221, v16, s[98:99]
	s_or_b64 exec, exec, s[100:101]
	s_mov_b64 s[10:11], 0xb0000
	s_andn2_b64 vcc, exec, s[40:41]
	s_cbranch_vccnz .LBB0_705
	s_andn2_b64 vcc, exec, s[42:43]
	s_cbranch_vccnz .LBB0_704
	s_barrier
	s_branch .LBB0_704

	.amdhsa_kernel _Z8mega_fwd4Args
		.amdhsa_group_segment_fixed_size 0
		.amdhsa_private_segment_fixed_size 0
		.amdhsa_kernarg_size 480
		.amdhsa_user_sgpr_count 2
		.amdhsa_user_sgpr_dispatch_ptr 0
		.amdhsa_user_sgpr_queue_ptr 0
		.amdhsa_user_sgpr_kernarg_segment_ptr 1
		.amdhsa_user_sgpr_dispatch_id 0
		.amdhsa_user_sgpr_kernarg_preload_length 0
		.amdhsa_user_sgpr_kernarg_preload_offset 0
		.amdhsa_user_sgpr_private_segment_size 0
		.amdhsa_uses_dynamic_stack 0
		.amdhsa_enable_private_segment 0
		.amdhsa_system_sgpr_workgroup_id_x 1
		.amdhsa_system_sgpr_workgroup_id_y 0
		.amdhsa_system_sgpr_workgroup_id_z 0
		.amdhsa_system_sgpr_workgroup_info 0
		.amdhsa_system_vgpr_workitem_id 2
		.amdhsa_next_free_vgpr 248
		.amdhsa_next_free_sgpr 102
		.amdhsa_accum_offset 248
		.amdhsa_reserve_vcc 1
		.amdhsa_float_round_mode_32 0
		.amdhsa_float_round_mode_16_64 0
		.amdhsa_float_denorm_mode_32 3
		.amdhsa_float_denorm_mode_16_64 3
		.amdhsa_dx10_clamp 1
		.amdhsa_ieee_mode 1
		.amdhsa_fp16_overflow 0
		.amdhsa_tg_split 0
		.amdhsa_exception_fp_ieee_invalid_op 0
		.amdhsa_exception_fp_denorm_src 0
		.amdhsa_exception_fp_ieee_div_zero 0
		.amdhsa_exception_fp_ieee_overflow 0
		.amdhsa_exception_fp_ieee_underflow 0
		.amdhsa_exception_fp_ieee_inexact 0
		.amdhsa_exception_int_div_zero 0
	.end_amdhsa_kernel

amdhsa.kernels:
  - .agpr_count:     0
    .args:
      - .offset:         0
        .size:           224
        .value_kind:     by_value
      - .offset:         224
        .size:           4
        .value_kind:     hidden_block_count_x
      - .offset:         228
        .size:           4
        .value_kind:     hidden_block_count_y
      - .offset:         232
        .size:           4
        .value_kind:     hidden_block_count_z
      - .offset:         236
        .size:           2
        .value_kind:     hidden_group_size_x
      - .offset:         238
        .size:           2
        .value_kind:     hidden_group_size_y
      - .offset:         240
        .size:           2
        .value_kind:     hidden_group_size_z
      - .offset:         242
        .size:           2
        .value_kind:     hidden_remainder_x
      - .offset:         244
        .size:           2
        .value_kind:     hidden_remainder_y
      - .offset:         246
        .size:           2
        .value_kind:     hidden_remainder_z
      - .offset:         264
        .size:           8
        .value_kind:     hidden_global_offset_x
      - .offset:         272
        .size:           8
        .value_kind:     hidden_global_offset_y
      - .offset:         280
        .size:           8
        .value_kind:     hidden_global_offset_z
      - .offset:         288
        .size:           2
        .value_kind:     hidden_grid_dims
      - .offset:         312
        .size:           8
        .value_kind:     hidden_multigrid_sync_arg
      - .offset:         344
        .size:           4
        .value_kind:     hidden_dynamic_lds_size
    .group_segment_fixed_size: 0
    .kernarg_segment_align: 8
    .kernarg_segment_size: 480
    .language:       OpenCL C
    .language_version:
      - 2
      - 0
    .max_flat_workgroup_size: 512
    .name:           _Z8mega_fwd4Args
    .private_segment_fixed_size: 0
    .sgpr_count:     108
    .sgpr_spill_count: 182
    .symbol:         _Z8mega_fwd4Args.kd
    .uniform_work_group_size: 1
    .uses_dynamic_stack: false
    .vgpr_count:     248
    .vgpr_spill_count: 0
    .wavefront_size: 64
